# 4-phase K-loop: s_setprio 0 moved after the end-of-cluster barrier
# speedup vs baseline: 1.0056x; 1.0056x over previous
.LBB0_919:
	s_add_i32 s42, s20, 2
	s_add_u32 s24, s18, 0x80
	s_addc_u32 s21, s19, 0
	s_add_i32 s43, 0, 0x10000
	v_add_u32_e32 v0, s43, v211
	s_waitcnt lgkmcnt(0)
	ds_read_b128 v[130:133], v0
	ds_read_b128 v[134:137], v0 offset:1024
	ds_read_b128 v[138:141], v0 offset:2048
	ds_read_b128 v[142:145], v0 offset:3072
	s_cmp_eq_u32 s66, s20
	s_cselect_b32 s20, s74, s24
	s_cselect_b32 s21, s75, s21
	s_cselect_b32 s25, s77, s39
	s_cselect_b32 s24, s76, s38
	s_add_i32 s44, 0, 0x14000
	v_add_u32_e32 v0, s44, v211
	v_lshl_add_u64 v[198:199], s[18:19], 0, v[184:185]
	s_add_i32 m0, s31, 0xc000
	ds_read_b128 v[232:235], v0
	ds_read_b128 v[236:239], v0 offset:1024
	ds_read_b128 v[240:243], v0 offset:2048
	ds_read_b128 v[244:247], v0 offset:3072
	global_load_lds_dwordx4 v[198:199], off
	v_lshl_add_u64 v[198:199], s[18:19], 0, v[182:183]
	s_add_i32 m0, s31, 0xe000
	s_nop 0
	global_load_lds_dwordx4 v[198:199], off
	ds_read_b128 v[146:149], v212
	ds_read_b128 v[150:153], v212 offset:1024
	ds_read_b128 v[154:157], v212 offset:2048
	ds_read_b128 v[158:161], v212 offset:3072
	ds_read_b128 v[186:189], v212 offset:4096
	ds_read_b128 v[190:193], v212 offset:5120
	s_waitcnt lgkmcnt(12)
	ds_read_b128 v[194:197], v212 offset:6144
	ds_read_b128 v[214:217], v212 offset:7168
	s_waitcnt vmcnt(8) lgkmcnt(0)
	s_barrier
	s_setprio 1
	v_mfma_f32_16x16x32_bf16 v[126:129], v[130:133], v[146:149], v[126:129]
	v_mfma_f32_16x16x32_bf16 v[122:125], v[138:141], v[146:149], v[122:125]
	v_mfma_f32_16x16x32_bf16 v[110:113], v[130:133], v[154:157], v[110:113]
	v_mfma_f32_16x16x32_bf16 v[106:109], v[138:141], v[154:157], v[106:109]
	v_mfma_f32_16x16x32_bf16 v[94:97], v[130:133], v[186:189], v[94:97]
	v_mfma_f32_16x16x32_bf16 v[90:93], v[138:141], v[186:189], v[90:93]
	v_mfma_f32_16x16x32_bf16 v[78:81], v[130:133], v[194:197], v[78:81]
	v_mfma_f32_16x16x32_bf16 v[74:77], v[138:141], v[194:197], v[74:77]
	v_mfma_f32_16x16x32_bf16 v[126:129], v[134:137], v[150:153], v[126:129]
	v_mfma_f32_16x16x32_bf16 v[122:125], v[142:145], v[150:153], v[122:125]
	v_mfma_f32_16x16x32_bf16 v[110:113], v[134:137], v[158:161], v[110:113]
	v_mfma_f32_16x16x32_bf16 v[106:109], v[142:145], v[158:161], v[106:109]
	v_mfma_f32_16x16x32_bf16 v[94:97], v[134:137], v[190:193], v[94:97]
	v_mfma_f32_16x16x32_bf16 v[90:93], v[142:145], v[190:193], v[90:93]
	v_mfma_f32_16x16x32_bf16 v[78:81], v[134:137], v[214:217], v[78:81]
	v_mfma_f32_16x16x32_bf16 v[74:77], v[142:145], v[214:217], v[74:77]
	v_mfma_f32_16x16x32_bf16 v[118:121], v[232:235], v[146:149], v[118:121]
	v_mfma_f32_16x16x32_bf16 v[114:117], v[240:243], v[146:149], v[114:117]
	v_mfma_f32_16x16x32_bf16 v[102:105], v[232:235], v[154:157], v[102:105]
	v_mfma_f32_16x16x32_bf16 v[98:101], v[240:243], v[154:157], v[98:101]
	v_mfma_f32_16x16x32_bf16 v[86:89], v[232:235], v[186:189], v[86:89]
	v_mfma_f32_16x16x32_bf16 v[82:85], v[240:243], v[186:189], v[82:85]
	v_mfma_f32_16x16x32_bf16 v[70:73], v[232:235], v[194:197], v[70:73]
	v_mfma_f32_16x16x32_bf16 v[66:69], v[240:243], v[194:197], v[66:69]
	v_mfma_f32_16x16x32_bf16 v[118:121], v[236:239], v[150:153], v[118:121]
	v_mfma_f32_16x16x32_bf16 v[114:117], v[244:247], v[150:153], v[114:117]
	v_mfma_f32_16x16x32_bf16 v[102:105], v[236:239], v[158:161], v[102:105]
	v_mfma_f32_16x16x32_bf16 v[98:101], v[244:247], v[158:161], v[98:101]
	v_mfma_f32_16x16x32_bf16 v[86:89], v[236:239], v[190:193], v[86:89]
	v_mfma_f32_16x16x32_bf16 v[82:85], v[244:247], v[190:193], v[82:85]
	v_mfma_f32_16x16x32_bf16 v[70:73], v[236:239], v[214:217], v[70:73]
	v_mfma_f32_16x16x32_bf16 v[66:69], v[244:247], v[214:217], v[66:69]
	s_barrier
	s_setprio 0
	ds_read_b128 v[146:149], v212 offset:16384
	ds_read_b128 v[150:153], v212 offset:17408
	ds_read_b128 v[154:157], v212 offset:18432
	ds_read_b128 v[158:161], v212 offset:19456
	ds_read_b128 v[186:189], v212 offset:20480
	ds_read_b128 v[190:193], v212 offset:21504
	ds_read_b128 v[194:197], v212 offset:22528
	ds_read_b128 v[214:217], v212 offset:23552
	s_add_i32 s43, s43, s30
	v_lshl_add_u64 v[198:199], s[24:25], 0, v[170:171]
	s_mov_b32 m0, s43
	v_lshl_add_u64 v[218:219], s[24:25], 0, v[174:175]
	global_load_lds_dwordx4 v[198:199], off
	s_add_i32 m0, s43, 0x2000
	s_nop 0
	global_load_lds_dwordx4 v[218:219], off
	s_mov_b32 m0, s31
	v_lshl_add_u64 v[248:249], s[20:21], 0, v[168:169]
	v_lshl_add_u64 v[250:251], s[20:21], 0, v[172:173]
	global_load_lds_dwordx4 v[248:249], off
	s_mov_b32 m0, s95
	s_nop 0
	global_load_lds_dwordx4 v[250:251], off
	s_add_u32 s24, s24, s60
	s_addc_u32 s25, s25, 0
	s_add_i32 s43, s44, s30
	v_lshl_add_u64 v[226:227], s[24:25], 0, v[170:171]
	s_mov_b32 m0, s43
	v_lshl_add_u64 v[228:229], s[24:25], 0, v[174:175]
	global_load_lds_dwordx4 v[226:227], off
	s_add_i32 m0, s43, 0x2000
	s_nop 0
	global_load_lds_dwordx4 v[228:229], off
	s_waitcnt vmcnt(8) lgkmcnt(0)
	s_barrier
	s_setprio 1
	v_mfma_f32_16x16x32_bf16 v[62:65], v[130:133], v[146:149], v[62:65]
	v_mfma_f32_16x16x32_bf16 v[58:61], v[138:141], v[146:149], v[58:61]
	v_mfma_f32_16x16x32_bf16 v[46:49], v[130:133], v[154:157], v[46:49]
	v_mfma_f32_16x16x32_bf16 v[42:45], v[138:141], v[154:157], v[42:45]
	v_mfma_f32_16x16x32_bf16 v[30:33], v[130:133], v[186:189], v[30:33]
	v_mfma_f32_16x16x32_bf16 v[26:29], v[138:141], v[186:189], v[26:29]
	v_mfma_f32_16x16x32_bf16 v[14:17], v[130:133], v[194:197], v[14:17]
	v_mfma_f32_16x16x32_bf16 v[10:13], v[138:141], v[194:197], v[10:13]
	v_mfma_f32_16x16x32_bf16 v[62:65], v[134:137], v[150:153], v[62:65]
	v_mfma_f32_16x16x32_bf16 v[58:61], v[142:145], v[150:153], v[58:61]
	v_mfma_f32_16x16x32_bf16 v[46:49], v[134:137], v[158:161], v[46:49]
	v_mfma_f32_16x16x32_bf16 v[42:45], v[142:145], v[158:161], v[42:45]
	v_mfma_f32_16x16x32_bf16 v[30:33], v[134:137], v[190:193], v[30:33]
	v_mfma_f32_16x16x32_bf16 v[26:29], v[142:145], v[190:193], v[26:29]
	v_mfma_f32_16x16x32_bf16 v[14:17], v[134:137], v[214:217], v[14:17]
	v_mfma_f32_16x16x32_bf16 v[10:13], v[142:145], v[214:217], v[10:13]
	v_mfma_f32_16x16x32_bf16 v[54:57], v[232:235], v[146:149], v[54:57]
	v_mfma_f32_16x16x32_bf16 v[50:53], v[240:243], v[146:149], v[50:53]
	v_mfma_f32_16x16x32_bf16 v[38:41], v[232:235], v[154:157], v[38:41]
	v_mfma_f32_16x16x32_bf16 v[34:37], v[240:243], v[154:157], v[34:37]
	v_mfma_f32_16x16x32_bf16 v[22:25], v[232:235], v[186:189], v[22:25]
	v_mfma_f32_16x16x32_bf16 v[18:21], v[240:243], v[186:189], v[18:21]
	v_mfma_f32_16x16x32_bf16 v[6:9], v[232:235], v[194:197], v[6:9]
	v_mfma_f32_16x16x32_bf16 v[2:5], v[240:243], v[194:197], v[2:5]
	v_mfma_f32_16x16x32_bf16 v[54:57], v[236:239], v[150:153], v[54:57]
	v_mfma_f32_16x16x32_bf16 v[50:53], v[244:247], v[150:153], v[50:53]
	v_mfma_f32_16x16x32_bf16 v[38:41], v[236:239], v[158:161], v[38:41]
	v_mfma_f32_16x16x32_bf16 v[34:37], v[244:247], v[158:161], v[34:37]
	v_mfma_f32_16x16x32_bf16 v[22:25], v[236:239], v[190:193], v[22:25]
	v_mfma_f32_16x16x32_bf16 v[18:21], v[244:247], v[190:193], v[18:21]
	v_mfma_f32_16x16x32_bf16 v[6:9], v[236:239], v[214:217], v[6:9]
	v_mfma_f32_16x16x32_bf16 v[2:5], v[244:247], v[214:217], v[2:5]
	s_barrier
	s_setprio 0
	s_add_u32 s20, s20, s60
	s_addc_u32 s21, s21, 0
	s_mov_b32 m0, s8
	v_lshl_add_u64 v[232:233], s[20:21], 0, v[168:169]
	s_add_i32 s24, 0, 0x18000
	v_add_u32_e32 v0, s24, v211
	global_load_lds_dwordx4 v[232:233], off
	v_lshl_add_u64 v[232:233], s[20:21], 0, v[172:173]
	s_mov_b32 m0, s9
	s_nop 0
	global_load_lds_dwordx4 v[232:233], off
	ds_read_b128 v[130:133], v0
	ds_read_b128 v[134:137], v0 offset:1024
	ds_read_b128 v[138:141], v0 offset:2048
	ds_read_b128 v[142:145], v0 offset:3072
	s_add_i32 s20, 0, 0x1c000
	s_add_i32 s21, s24, s30
	v_add_u32_e32 v0, s20, v211
	ds_read_b128 v[232:235], v0
	ds_read_b128 v[236:239], v0 offset:1024
	ds_read_b128 v[240:243], v0 offset:2048
	ds_read_b128 v[244:247], v0 offset:3072
	ds_read_b128 v[146:149], v212 offset:32768
	ds_read_b128 v[150:153], v212 offset:33792
	ds_read_b128 v[154:157], v212 offset:34816
	ds_read_b128 v[158:161], v212 offset:35840
	ds_read_b128 v[186:189], v212 offset:36864
	ds_read_b128 v[190:193], v212 offset:37888
	s_waitcnt lgkmcnt(12)
	ds_read_b128 v[194:197], v212 offset:38912
	ds_read_b128 v[214:217], v212 offset:39936
	s_waitcnt vmcnt(8) lgkmcnt(0)
	s_barrier
	s_setprio 1
	v_mfma_f32_16x16x32_bf16 v[126:129], v[130:133], v[146:149], v[126:129]
	v_mfma_f32_16x16x32_bf16 v[122:125], v[138:141], v[146:149], v[122:125]
	v_mfma_f32_16x16x32_bf16 v[110:113], v[130:133], v[154:157], v[110:113]
	v_mfma_f32_16x16x32_bf16 v[106:109], v[138:141], v[154:157], v[106:109]
	v_mfma_f32_16x16x32_bf16 v[94:97], v[130:133], v[186:189], v[94:97]
	v_mfma_f32_16x16x32_bf16 v[90:93], v[138:141], v[186:189], v[90:93]
	v_mfma_f32_16x16x32_bf16 v[78:81], v[130:133], v[194:197], v[78:81]
	v_mfma_f32_16x16x32_bf16 v[74:77], v[138:141], v[194:197], v[74:77]
	v_mfma_f32_16x16x32_bf16 v[126:129], v[134:137], v[150:153], v[126:129]
	v_mfma_f32_16x16x32_bf16 v[122:125], v[142:145], v[150:153], v[122:125]
	v_mfma_f32_16x16x32_bf16 v[110:113], v[134:137], v[158:161], v[110:113]
	v_mfma_f32_16x16x32_bf16 v[106:109], v[142:145], v[158:161], v[106:109]
	v_mfma_f32_16x16x32_bf16 v[94:97], v[134:137], v[190:193], v[94:97]
	v_mfma_f32_16x16x32_bf16 v[90:93], v[142:145], v[190:193], v[90:93]
	v_mfma_f32_16x16x32_bf16 v[78:81], v[134:137], v[214:217], v[78:81]
	v_mfma_f32_16x16x32_bf16 v[74:77], v[142:145], v[214:217], v[74:77]
	v_mfma_f32_16x16x32_bf16 v[118:121], v[232:235], v[146:149], v[118:121]
	v_mfma_f32_16x16x32_bf16 v[114:117], v[240:243], v[146:149], v[114:117]
	v_mfma_f32_16x16x32_bf16 v[102:105], v[232:235], v[154:157], v[102:105]
	v_mfma_f32_16x16x32_bf16 v[98:101], v[240:243], v[154:157], v[98:101]
	v_mfma_f32_16x16x32_bf16 v[86:89], v[232:235], v[186:189], v[86:89]
	v_mfma_f32_16x16x32_bf16 v[82:85], v[240:243], v[186:189], v[82:85]
	v_mfma_f32_16x16x32_bf16 v[70:73], v[232:235], v[194:197], v[70:73]
	v_mfma_f32_16x16x32_bf16 v[66:69], v[240:243], v[194:197], v[66:69]
	v_mfma_f32_16x16x32_bf16 v[118:121], v[236:239], v[150:153], v[118:121]
	v_mfma_f32_16x16x32_bf16 v[114:117], v[244:247], v[150:153], v[114:117]
	v_mfma_f32_16x16x32_bf16 v[102:105], v[236:239], v[158:161], v[102:105]
	v_mfma_f32_16x16x32_bf16 v[98:101], v[244:247], v[158:161], v[98:101]
	v_mfma_f32_16x16x32_bf16 v[86:89], v[236:239], v[190:193], v[86:89]
	v_mfma_f32_16x16x32_bf16 v[82:85], v[244:247], v[190:193], v[82:85]
	v_mfma_f32_16x16x32_bf16 v[70:73], v[236:239], v[214:217], v[70:73]
	v_mfma_f32_16x16x32_bf16 v[66:69], v[244:247], v[214:217], v[66:69]
	s_barrier
	s_setprio 0
	ds_read_b128 v[146:149], v212 offset:49152
	ds_read_b128 v[150:153], v212 offset:50176
	ds_read_b128 v[154:157], v212 offset:51200
	ds_read_b128 v[158:161], v212 offset:52224
	ds_read_b128 v[186:189], v212 offset:53248
	ds_read_b128 v[190:193], v212 offset:54272
	ds_read_b128 v[194:197], v212 offset:55296
	ds_read_b128 v[214:217], v212 offset:56320
	v_lshl_add_u64 v[198:199], v[198:199], 0, s[16:17]
	s_mov_b32 m0, s21
	v_lshl_add_u64 v[218:219], v[218:219], 0, s[16:17]
	global_load_lds_dwordx4 v[198:199], off
	s_add_i32 m0, s21, 0x2000
	s_nop 0
	global_load_lds_dwordx4 v[218:219], off
	s_mov_b32 m0, s97
	v_lshl_add_u64 v[248:249], v[248:249], 0, s[16:17]
	v_lshl_add_u64 v[250:251], v[250:251], 0, s[16:17]
	global_load_lds_dwordx4 v[248:249], off
	s_mov_b32 m0, s90
	s_nop 0
	global_load_lds_dwordx4 v[250:251], off
	s_add_i32 s20, s20, s30
	v_lshl_add_u64 v[226:227], v[226:227], 0, s[16:17]
	s_mov_b32 m0, s20
	v_lshl_add_u64 v[228:229], v[228:229], 0, s[16:17]
	global_load_lds_dwordx4 v[226:227], off
	s_add_i32 m0, s20, 0x2000
	s_nop 0
	global_load_lds_dwordx4 v[228:229], off
	s_waitcnt vmcnt(8) lgkmcnt(0)
	s_barrier
	s_setprio 1
	v_mfma_f32_16x16x32_bf16 v[62:65], v[130:133], v[146:149], v[62:65]
	v_mfma_f32_16x16x32_bf16 v[58:61], v[138:141], v[146:149], v[58:61]
	v_mfma_f32_16x16x32_bf16 v[46:49], v[130:133], v[154:157], v[46:49]
	v_mfma_f32_16x16x32_bf16 v[42:45], v[138:141], v[154:157], v[42:45]
	v_mfma_f32_16x16x32_bf16 v[30:33], v[130:133], v[186:189], v[30:33]
	v_mfma_f32_16x16x32_bf16 v[26:29], v[138:141], v[186:189], v[26:29]
	v_mfma_f32_16x16x32_bf16 v[14:17], v[130:133], v[194:197], v[14:17]
	v_mfma_f32_16x16x32_bf16 v[10:13], v[138:141], v[194:197], v[10:13]
	v_mfma_f32_16x16x32_bf16 v[62:65], v[134:137], v[150:153], v[62:65]
	v_mfma_f32_16x16x32_bf16 v[58:61], v[142:145], v[150:153], v[58:61]
	v_mfma_f32_16x16x32_bf16 v[46:49], v[134:137], v[158:161], v[46:49]
	v_mfma_f32_16x16x32_bf16 v[42:45], v[142:145], v[158:161], v[42:45]
	v_mfma_f32_16x16x32_bf16 v[30:33], v[134:137], v[190:193], v[30:33]
	v_mfma_f32_16x16x32_bf16 v[26:29], v[142:145], v[190:193], v[26:29]
	v_mfma_f32_16x16x32_bf16 v[14:17], v[134:137], v[214:217], v[14:17]
	v_mfma_f32_16x16x32_bf16 v[10:13], v[142:145], v[214:217], v[10:13]
	v_mfma_f32_16x16x32_bf16 v[54:57], v[232:235], v[146:149], v[54:57]
	v_mfma_f32_16x16x32_bf16 v[50:53], v[240:243], v[146:149], v[50:53]
	v_mfma_f32_16x16x32_bf16 v[38:41], v[232:235], v[154:157], v[38:41]
	v_mfma_f32_16x16x32_bf16 v[34:37], v[240:243], v[154:157], v[34:37]
	v_mfma_f32_16x16x32_bf16 v[22:25], v[232:235], v[186:189], v[22:25]
	v_mfma_f32_16x16x32_bf16 v[18:21], v[240:243], v[186:189], v[18:21]
	v_mfma_f32_16x16x32_bf16 v[6:9], v[232:235], v[194:197], v[6:9]
	v_mfma_f32_16x16x32_bf16 v[2:5], v[240:243], v[194:197], v[2:5]
	v_mfma_f32_16x16x32_bf16 v[54:57], v[236:239], v[150:153], v[54:57]
	v_mfma_f32_16x16x32_bf16 v[50:53], v[244:247], v[150:153], v[50:53]
	v_mfma_f32_16x16x32_bf16 v[38:41], v[236:239], v[158:161], v[38:41]
	v_mfma_f32_16x16x32_bf16 v[34:37], v[244:247], v[158:161], v[34:37]
	v_mfma_f32_16x16x32_bf16 v[22:25], v[236:239], v[190:193], v[22:25]
	v_mfma_f32_16x16x32_bf16 v[18:21], v[244:247], v[190:193], v[18:21]
	v_mfma_f32_16x16x32_bf16 v[6:9], v[236:239], v[214:217], v[6:9]
	v_mfma_f32_16x16x32_bf16 v[2:5], v[244:247], v[214:217], v[2:5]
	s_add_u32 s38, s38, 0x100
	s_addc_u32 s39, s39, 0
	s_add_u32 s18, s18, 0x100
	s_addc_u32 s19, s19, 0
	s_cmp_ge_u32 s42, s91
	s_mov_b32 s20, s42
	s_barrier
	s_setprio 0
	s_cbranch_scc0 .LBB0_919
	s_branch .Lkloop_done
.Lkloop_narrow:
	s_add_i32 s42, s20, 2
	s_add_u32 s24, s18, 0x80
	s_addc_u32 s21, s19, 0
	s_add_i32 s43, 0, 0x10000
	v_add_u32_e32 v0, s43, v211
	s_waitcnt lgkmcnt(0)
	ds_read_b128 v[130:133], v0
	ds_read_b128 v[134:137], v0 offset:1024
	ds_read_b128 v[138:141], v0 offset:2048
	ds_read_b128 v[142:145], v0 offset:3072
	s_cmp_eq_u32 s66, s20
	s_cselect_b32 s20, s74, s24
	s_cselect_b32 s21, s75, s21
	s_cselect_b32 s25, s77, s39
	s_cselect_b32 s24, s76, s38
	s_add_i32 s44, 0, 0x14000
	v_add_u32_e32 v0, s44, v211
	v_lshl_add_u64 v[198:199], s[18:19], 0, v[184:185]
	s_add_i32 m0, s31, 0xc000
	global_load_lds_dwordx4 v[198:199], off
	v_lshl_add_u64 v[198:199], s[18:19], 0, v[182:183]
	s_add_i32 m0, s31, 0xe000
	s_nop 0
	global_load_lds_dwordx4 v[198:199], off
	ds_read_b128 v[146:149], v212
	ds_read_b128 v[150:153], v212 offset:1024
	ds_read_b128 v[154:157], v212 offset:2048
	ds_read_b128 v[158:161], v212 offset:3072
	ds_read_b128 v[186:189], v212 offset:4096
	ds_read_b128 v[190:193], v212 offset:5120
	s_waitcnt lgkmcnt(12)
	ds_read_b128 v[194:197], v212 offset:6144
	ds_read_b128 v[214:217], v212 offset:7168
	s_waitcnt vmcnt(8) lgkmcnt(0)
	s_barrier
	s_setprio 1
	v_mfma_f32_16x16x32_bf16 v[126:129], v[130:133], v[146:149], v[126:129]
	v_mfma_f32_16x16x32_bf16 v[122:125], v[138:141], v[146:149], v[122:125]
	v_mfma_f32_16x16x32_bf16 v[110:113], v[130:133], v[154:157], v[110:113]
	v_mfma_f32_16x16x32_bf16 v[106:109], v[138:141], v[154:157], v[106:109]
	v_mfma_f32_16x16x32_bf16 v[94:97], v[130:133], v[186:189], v[94:97]
	v_mfma_f32_16x16x32_bf16 v[90:93], v[138:141], v[186:189], v[90:93]
	v_mfma_f32_16x16x32_bf16 v[78:81], v[130:133], v[194:197], v[78:81]
	v_mfma_f32_16x16x32_bf16 v[74:77], v[138:141], v[194:197], v[74:77]
	v_mfma_f32_16x16x32_bf16 v[126:129], v[134:137], v[150:153], v[126:129]
	v_mfma_f32_16x16x32_bf16 v[122:125], v[142:145], v[150:153], v[122:125]
	v_mfma_f32_16x16x32_bf16 v[110:113], v[134:137], v[158:161], v[110:113]
	v_mfma_f32_16x16x32_bf16 v[106:109], v[142:145], v[158:161], v[106:109]
	v_mfma_f32_16x16x32_bf16 v[94:97], v[134:137], v[190:193], v[94:97]
	v_mfma_f32_16x16x32_bf16 v[90:93], v[142:145], v[190:193], v[90:93]
	v_mfma_f32_16x16x32_bf16 v[78:81], v[134:137], v[214:217], v[78:81]
	v_mfma_f32_16x16x32_bf16 v[74:77], v[142:145], v[214:217], v[74:77]
	s_barrier
	s_setprio 0
	ds_read_b128 v[146:149], v212 offset:16384
	ds_read_b128 v[150:153], v212 offset:17408
	ds_read_b128 v[154:157], v212 offset:18432
	ds_read_b128 v[158:161], v212 offset:19456
	ds_read_b128 v[186:189], v212 offset:20480
	ds_read_b128 v[190:193], v212 offset:21504
	ds_read_b128 v[194:197], v212 offset:22528
	ds_read_b128 v[214:217], v212 offset:23552
	s_add_i32 s43, s43, s30
	v_lshl_add_u64 v[198:199], s[24:25], 0, v[170:171]
	s_mov_b32 m0, s43
	v_lshl_add_u64 v[218:219], s[24:25], 0, v[174:175]
	global_load_lds_dwordx4 v[198:199], off
	s_add_i32 m0, s43, 0x2000
	s_nop 0
	global_load_lds_dwordx4 v[218:219], off
	s_mov_b32 m0, s31
	v_lshl_add_u64 v[248:249], s[20:21], 0, v[168:169]
	v_lshl_add_u64 v[250:251], s[20:21], 0, v[172:173]
	global_load_lds_dwordx4 v[248:249], off
	s_mov_b32 m0, s95
	s_nop 0
	global_load_lds_dwordx4 v[250:251], off
	s_add_u32 s24, s24, s60
	s_addc_u32 s25, s25, 0
	s_add_i32 s43, s44, s30
	v_lshl_add_u64 v[226:227], s[24:25], 0, v[170:171]
	s_mov_b32 m0, s43
	v_lshl_add_u64 v[228:229], s[24:25], 0, v[174:175]
	global_load_lds_dwordx4 v[226:227], off
	s_add_i32 m0, s43, 0x2000
	s_nop 0
	global_load_lds_dwordx4 v[228:229], off
	s_waitcnt vmcnt(8) lgkmcnt(0)
	s_barrier
	s_setprio 1
	v_mfma_f32_16x16x32_bf16 v[62:65], v[130:133], v[146:149], v[62:65]
	v_mfma_f32_16x16x32_bf16 v[58:61], v[138:141], v[146:149], v[58:61]
	v_mfma_f32_16x16x32_bf16 v[46:49], v[130:133], v[154:157], v[46:49]
	v_mfma_f32_16x16x32_bf16 v[42:45], v[138:141], v[154:157], v[42:45]
	v_mfma_f32_16x16x32_bf16 v[30:33], v[130:133], v[186:189], v[30:33]
	v_mfma_f32_16x16x32_bf16 v[26:29], v[138:141], v[186:189], v[26:29]
	v_mfma_f32_16x16x32_bf16 v[14:17], v[130:133], v[194:197], v[14:17]
	v_mfma_f32_16x16x32_bf16 v[10:13], v[138:141], v[194:197], v[10:13]
	v_mfma_f32_16x16x32_bf16 v[62:65], v[134:137], v[150:153], v[62:65]
	v_mfma_f32_16x16x32_bf16 v[58:61], v[142:145], v[150:153], v[58:61]
	v_mfma_f32_16x16x32_bf16 v[46:49], v[134:137], v[158:161], v[46:49]
	v_mfma_f32_16x16x32_bf16 v[42:45], v[142:145], v[158:161], v[42:45]
	v_mfma_f32_16x16x32_bf16 v[30:33], v[134:137], v[190:193], v[30:33]
	v_mfma_f32_16x16x32_bf16 v[26:29], v[142:145], v[190:193], v[26:29]
	v_mfma_f32_16x16x32_bf16 v[14:17], v[134:137], v[214:217], v[14:17]
	v_mfma_f32_16x16x32_bf16 v[10:13], v[142:145], v[214:217], v[10:13]
	s_barrier
	s_setprio 0
	s_add_u32 s20, s20, s60
	s_addc_u32 s21, s21, 0
	s_mov_b32 m0, s8
	v_lshl_add_u64 v[232:233], s[20:21], 0, v[168:169]
	s_add_i32 s24, 0, 0x18000
	v_add_u32_e32 v0, s24, v211
	global_load_lds_dwordx4 v[232:233], off
	v_lshl_add_u64 v[232:233], s[20:21], 0, v[172:173]
	s_mov_b32 m0, s9
	s_nop 0
	global_load_lds_dwordx4 v[232:233], off
	ds_read_b128 v[130:133], v0
	ds_read_b128 v[134:137], v0 offset:1024
	ds_read_b128 v[138:141], v0 offset:2048
	ds_read_b128 v[142:145], v0 offset:3072
	s_add_i32 s20, 0, 0x1c000
	s_add_i32 s21, s24, s30
	v_add_u32_e32 v0, s20, v211
	ds_read_b128 v[146:149], v212 offset:32768
	ds_read_b128 v[150:153], v212 offset:33792
	ds_read_b128 v[154:157], v212 offset:34816
	ds_read_b128 v[158:161], v212 offset:35840
	ds_read_b128 v[186:189], v212 offset:36864
	ds_read_b128 v[190:193], v212 offset:37888
	s_waitcnt lgkmcnt(12)
	ds_read_b128 v[194:197], v212 offset:38912
	ds_read_b128 v[214:217], v212 offset:39936
	s_waitcnt vmcnt(8) lgkmcnt(0)
	s_barrier
	s_setprio 1
	v_mfma_f32_16x16x32_bf16 v[126:129], v[130:133], v[146:149], v[126:129]
	v_mfma_f32_16x16x32_bf16 v[122:125], v[138:141], v[146:149], v[122:125]
	v_mfma_f32_16x16x32_bf16 v[110:113], v[130:133], v[154:157], v[110:113]
	v_mfma_f32_16x16x32_bf16 v[106:109], v[138:141], v[154:157], v[106:109]
	v_mfma_f32_16x16x32_bf16 v[94:97], v[130:133], v[186:189], v[94:97]
	v_mfma_f32_16x16x32_bf16 v[90:93], v[138:141], v[186:189], v[90:93]
	v_mfma_f32_16x16x32_bf16 v[78:81], v[130:133], v[194:197], v[78:81]
	v_mfma_f32_16x16x32_bf16 v[74:77], v[138:141], v[194:197], v[74:77]
	v_mfma_f32_16x16x32_bf16 v[126:129], v[134:137], v[150:153], v[126:129]
	v_mfma_f32_16x16x32_bf16 v[122:125], v[142:145], v[150:153], v[122:125]
	v_mfma_f32_16x16x32_bf16 v[110:113], v[134:137], v[158:161], v[110:113]
	v_mfma_f32_16x16x32_bf16 v[106:109], v[142:145], v[158:161], v[106:109]
	v_mfma_f32_16x16x32_bf16 v[94:97], v[134:137], v[190:193], v[94:97]
	v_mfma_f32_16x16x32_bf16 v[90:93], v[142:145], v[190:193], v[90:93]
	v_mfma_f32_16x16x32_bf16 v[78:81], v[134:137], v[214:217], v[78:81]
	v_mfma_f32_16x16x32_bf16 v[74:77], v[142:145], v[214:217], v[74:77]
	s_barrier
	s_setprio 0
	ds_read_b128 v[146:149], v212 offset:49152
	ds_read_b128 v[150:153], v212 offset:50176
	ds_read_b128 v[154:157], v212 offset:51200
	ds_read_b128 v[158:161], v212 offset:52224
	ds_read_b128 v[186:189], v212 offset:53248
	ds_read_b128 v[190:193], v212 offset:54272
	ds_read_b128 v[194:197], v212 offset:55296
	ds_read_b128 v[214:217], v212 offset:56320
	v_lshl_add_u64 v[198:199], v[198:199], 0, s[16:17]
	s_mov_b32 m0, s21
	v_lshl_add_u64 v[218:219], v[218:219], 0, s[16:17]
	global_load_lds_dwordx4 v[198:199], off
	s_add_i32 m0, s21, 0x2000
	s_nop 0
	global_load_lds_dwordx4 v[218:219], off
	s_mov_b32 m0, s97
	v_lshl_add_u64 v[248:249], v[248:249], 0, s[16:17]
	v_lshl_add_u64 v[250:251], v[250:251], 0, s[16:17]
	global_load_lds_dwordx4 v[248:249], off
	s_mov_b32 m0, s90
	s_nop 0
	global_load_lds_dwordx4 v[250:251], off
	s_add_i32 s20, s20, s30
	v_lshl_add_u64 v[226:227], v[226:227], 0, s[16:17]
	s_mov_b32 m0, s20
	v_lshl_add_u64 v[228:229], v[228:229], 0, s[16:17]
	global_load_lds_dwordx4 v[226:227], off
	s_add_i32 m0, s20, 0x2000
	s_nop 0
	global_load_lds_dwordx4 v[228:229], off
	s_waitcnt vmcnt(8) lgkmcnt(0)
	s_barrier
	s_setprio 1
	v_mfma_f32_16x16x32_bf16 v[62:65], v[130:133], v[146:149], v[62:65]
	v_mfma_f32_16x16x32_bf16 v[58:61], v[138:141], v[146:149], v[58:61]
	v_mfma_f32_16x16x32_bf16 v[46:49], v[130:133], v[154:157], v[46:49]
	v_mfma_f32_16x16x32_bf16 v[42:45], v[138:141], v[154:157], v[42:45]
	v_mfma_f32_16x16x32_bf16 v[30:33], v[130:133], v[186:189], v[30:33]
	v_mfma_f32_16x16x32_bf16 v[26:29], v[138:141], v[186:189], v[26:29]
	v_mfma_f32_16x16x32_bf16 v[14:17], v[130:133], v[194:197], v[14:17]
	v_mfma_f32_16x16x32_bf16 v[10:13], v[138:141], v[194:197], v[10:13]
	v_mfma_f32_16x16x32_bf16 v[62:65], v[134:137], v[150:153], v[62:65]
	v_mfma_f32_16x16x32_bf16 v[58:61], v[142:145], v[150:153], v[58:61]
	v_mfma_f32_16x16x32_bf16 v[46:49], v[134:137], v[158:161], v[46:49]
	v_mfma_f32_16x16x32_bf16 v[42:45], v[142:145], v[158:161], v[42:45]
	v_mfma_f32_16x16x32_bf16 v[30:33], v[134:137], v[190:193], v[30:33]
	v_mfma_f32_16x16x32_bf16 v[26:29], v[142:145], v[190:193], v[26:29]
	v_mfma_f32_16x16x32_bf16 v[14:17], v[134:137], v[214:217], v[14:17]
	v_mfma_f32_16x16x32_bf16 v[10:13], v[142:145], v[214:217], v[10:13]
	s_add_u32 s38, s38, 0x100
	s_addc_u32 s39, s39, 0
	s_add_u32 s18, s18, 0x100
	s_addc_u32 s19, s19, 0
	s_cmp_ge_u32 s42, s91
	s_mov_b32 s20, s42
	s_barrier
	s_setprio 0
	s_cbranch_scc0 .Lkloop_narrow
